# rw_scan: per-iteration address math replaced by incremental row + saddr loads; transpose-reduce via bank-masked DPP
# speedup vs baseline: 1.0440x; 1.0169x over previous
.LBB0_768:
	s_lshl_b32 s0, s8, 5
	s_and_b32 s0, s0, 0xe0
	s_ashr_i32 s11, s8, 3
	s_add_i32 s0, s0, s11
	s_bfe_u32 s9, s0, 0x40003
	s_lshl_b32 s6, s9, 8
	v_lshl_add_u64 v[0:1], v[52:53], 0, s[6:7]
	v_lshl_add_u64 v[4:5], v[54:55], 0, s[6:7]
	global_load_dwordx4 v[0:3], v[0:1], off
	s_bfe_u32 s6, s11, 0x10002
	global_load_dwordx4 v[4:7], v[4:5], off
	s_ashr_i32 s12, s0, 7
	s_cmp_eq_u32 s6, 0
	s_cselect_b64 s[46:47], -1, 0
	s_and_saveexec_b64 s[0:1], s[36:37]
	s_xor_b64 s[0:1], exec, s[0:1]
	v_cndmask_b32_e64 v8, v59, v51, s[46:47]
	s_lshl_b32 s10, s12, 13
	s_lshl_b32 s13, s12, 8
	v_add_u32_e32 v8, s10, v8
	v_mov_b32_e32 v10, s13
	v_mov_b32_e32 v98, s10
	s_or_saveexec_b64 s[0:1], s[0:1]
	s_lshl_b32 s10, s9, 6
	s_xor_b64 exec, exec, s[0:1]
	v_cndmask_b32_e64 v8, v71, v49, s[46:47]
	s_lshl_b32 s13, s12, 8
	v_add_u32_e32 v8, s13, v8
	s_lshl_b32 s12, s12, 13
	v_add_u32_e32 v8, 0x4000, v8
	v_mov_b32_e32 v10, s13
	v_mov_b32_e32 v98, s12
	s_or_b64 exec, exec, s[0:1]
	v_mov_b32_e32 v131, v8
	s_lshl_b32 s0, s6, 5
	s_sub_i32 s0, 16, s0
	v_mov_b32_e32 v132, s0
	v_sub_u32_e32 v133, 0x1fff, v49
	v_cndmask_b32_e64 v133, v133, v49, s[46:47]
	v_add_u32_e32 v133, v98, v133
	s_lshl_b32 s0, s9, 2
	v_mov_b32_e32 v134, s0
	s_mul_i32 s6, s6, 0x2100000
	v_ashrrev_i32_e32 v9, 31, v8
	s_add_u32 s24, s86, s6
	v_or_b32_e32 v58, s10, v50
	v_lshlrev_b64 v[12:13], 11, v[8:9]
	s_addc_u32 s25, s87, 0
	v_readlane_b32 s0, v182, 23
	v_lshl_or_b32 v14, v58, 1, v12
	v_mov_b32_e32 v15, v13
	v_readlane_b32 s1, v182, 24
	s_add_u32 s20, s0, s6
	v_lshl_add_u64 v[16:17], s[2:3], 0, v[14:15]
	v_lshl_or_b32 v8, v8, 4, s9
	s_addc_u32 s21, s1, 0
	global_load_dwordx2 v[16:17], v[16:17], off
	v_ashrrev_i32_e32 v9, 31, v8
	v_lshl_add_u64 v[18:19], s[90:91], 0, v[14:15]
	v_lshl_add_u64 v[20:21], s[20:21], 0, v[14:15]
	v_lshl_add_u64 v[14:15], s[24:25], 0, v[14:15]
	v_lshl_add_u64 v[8:9], v[8:9], 2, s[74:75]
	global_load_dwordx2 v[18:19], v[18:19], off
	s_add_u32 vcc_lo, s22, s6
	global_load_dwordx2 v[22:23], v[14:15], off
	v_readlane_b32 s12, v181, 42
	global_load_dword v8, v[8:9], off
	s_addc_u32 vcc_hi, s23, 0
	global_load_dwordx2 v[20:21], v[20:21], off
	s_lshl_b32 s0, s11, 4
	v_readlane_b32 s13, v181, 43
	s_and_b32 s11, s0, 48
	s_lshl_b32 s6, s10, 1
	v_lshl_add_u64 v[12:13], s[12:13], 0, v[12:13]
	v_lshl_add_u64 v[12:13], v[12:13], 0, s[6:7]
	s_lshl_b32 s0, s11, 1
	s_mov_b32 s1, s7
	v_lshl_add_u64 v[12:13], v[12:13], 0, s[0:1]
	v_lshl_add_u64 v[24:25], v[12:13], 0, v[68:69]
	s_add_i32 s10, s10, s11
	s_add_u32 s1, s12, s6
	s_addc_u32 s6, s13, 0
	s_add_u32 s0, s1, s0
	s_addc_u32 s1, s6, 0
	v_lshl_add_u64 v[60:61], s[0:1], 0, v[68:69]
	v_add_u32_e32 v99, 0x4000, v10
	s_mov_b32 s6, 0
	v_mov_b32_e32 v100, v97
	v_mov_b32_e32 v101, v96
	s_waitcnt vmcnt(4)
	v_lshlrev_b32_e32 v26, 16, v16
	v_and_b32_e32 v27, 0xffff0000, v16
	v_pk_mul_f32 v[12:13], v[0:1], v[26:27]
	s_waitcnt vmcnt(2)
	v_alignbit_b32 v11, v23, v22, 16
	s_waitcnt vmcnt(1)
	v_pk_mul_f32 v[30:31], v[12:13], v[8:9] op_sel_hi:[1,0]
	v_alignbit_b32 v9, v17, v16, 16
	v_and_b32_e32 v17, 0xffff0000, v17
	v_and_b32_e32 v16, 0xffff0000, v9
	v_pk_mul_f32 v[14:15], v[2:3], v[16:17]
	v_xor_b32_e32 v13, 0x80000000, v31
	v_pk_mul_f32 v[8:9], v[8:9], v[14:15] op_sel_hi:[0,1]
	v_xor_b32_e32 v12, 0x80000000, v30
	v_xor_b32_e32 v15, 0x80000000, v9
	v_xor_b32_e32 v14, 0x80000000, v8
	ds_write_b128 v81, v[12:15]
	v_lshlrev_b32_e32 v12, 16, v22
	v_and_b32_e32 v13, 0xffff0000, v22
	v_and_b32_e32 v15, 0xffff0000, v23
	v_and_b32_e32 v14, 0xffff0000, v11
	s_waitcnt vmcnt(0)
	v_alignbit_b32 v11, v21, v20, 16
	v_lshlrev_b32_e32 v28, 16, v20
	v_and_b32_e32 v29, 0xffff0000, v20
	v_pk_add_f32 v[12:13], v[12:13], 1.0 op_sel_hi:[1,0] neg_lo:[1,0] neg_hi:[1,0]
	v_pk_add_f32 v[14:15], v[14:15], 1.0 op_sel_hi:[1,0] neg_lo:[1,0] neg_hi:[1,0]
	v_and_b32_e32 v21, 0xffff0000, v21
	v_and_b32_e32 v20, 0xffff0000, v11
	ds_write_b128 v81, v[12:15] offset:256
	v_pk_mul_f32 v[14:15], v[8:9], v[20:21]
	v_pk_add_f32 v[8:9], v[28:29], -1.0 op_sel_hi:[1,0]
	v_pk_mul_f32 v[12:13], v[30:31], v[28:29]
	v_pk_fma_f32 v[8:9], v[4:5], v[8:9], 1.0 op_sel_hi:[1,1,0]
	ds_write_b128 v81, v[12:15] offset:512
	v_pk_mul_f32 v[12:13], v[8:9], v[26:27]
	v_pk_add_f32 v[8:9], v[20:21], -1.0 op_sel_hi:[1,0]
	s_nop 0
	v_pk_fma_f32 v[8:9], v[6:7], v[8:9], 1.0 op_sel_hi:[1,1,0]
	s_nop 0
	v_pk_mul_f32 v[14:15], v[8:9], v[16:17]
	v_alignbit_b32 v8, v19, v18, 16
	ds_write_b128 v81, v[12:15] offset:768
	v_and_b32_e32 v14, 0xffff0000, v8
	global_load_ushort v8, v[24:25], off
	v_and_b32_e32 v15, 0xffff0000, v19
	v_lshlrev_b32_e32 v12, 16, v18
	v_and_b32_e32 v13, 0xffff0000, v18
	ds_write_b128 v81, v[12:15] offset:1024
	s_waitcnt vmcnt(0)
	v_lshlrev_b32_e32 v8, 16, v8
	ds_write_b32 v88, v8 offset:1280
	v_add_u32_e32 v8, s10, v89
	v_ashrrev_i32_e32 v9, 31, v8
	v_lshl_add_u64 v[56:57], v[8:9], 1, vcc
	v_mov_b32_e32 v8, 0
	s_mov_b32 s10, 0
	v_mov_b32_e32 v9, v8
	v_mov_b32_e32 v10, v8
	v_mov_b32_e32 v11, v8
	v_lshlrev_b32_e32 v58, 1, v58
	v_readlane_b32 s100, v181, 42
	v_readlane_b32 s101, v181, 43
	s_nop 1
	v_subrev_u32_e32 v60, s100, v60
	s_waitcnt lgkmcnt(0)
	s_barrier
	s_branch .LBB0_774

.LBB0_774:
	v_add_u32_e32 v131, v132, v131
	s_cmp_eq_u32 s10, 15
	s_cbranch_scc0 .Lscan_top_nox
	v_mov_b32_e32 v131, v133
.Lscan_top_nox:
	s_and_b32 s11, s10, 1
	v_lshl_add_u32 v13, v131, 11, v58
	v_lshl_add_u32 v14, v131, 6, v134
	v_lshl_add_u32 v15, v131, 11, v60
	s_mul_i32 s0, s11, 0x5400
	global_load_dwordx2 v[74:75], v13, s[2:3]
	global_load_dwordx2 v[62:63], v13, s[90:91]
	global_load_dwordx2 v[76:77], v13, s[24:25]
	global_load_dword v78, v14, s[74:75]
	global_load_dwordx2 v[72:73], v13, s[20:21]
	global_load_ushort v102, v15, s[100:101]
	s_add_i32 s0, s0, 16
	v_lshl_add_u32 v126, v87, 2, s0
	v_add3_u32 v124, s0, v91, v92
	ds_read_b32 v204, v124 offset:1280
	ds_read_b128 v[184:187], v126 offset:0
	ds_read_b128 v[196:199], v126 offset:768
	ds_read_b128 v[188:191], v126 offset:256
	ds_read_b128 v[200:203], v126 offset:1024
	ds_read_b128 v[192:195], v126 offset:512
	ds_read_b32 v226, v124 offset:2624
	ds_read_b128 v[206:209], v126 offset:1344
	ds_read_b128 v[218:221], v126 offset:2112
	ds_read_b128 v[210:213], v126 offset:1600
	ds_read_b128 v[222:225], v126 offset:2368
	ds_read_b128 v[214:217], v126 offset:1856
	s_waitcnt lgkmcnt(6)
	v_pk_mul_f32 v[250:251], v[8:9], v[184:185]
	v_pk_mul_f32 v[252:253], v[204:205], v[196:197] op_sel_hi:[0,1]
	v_pk_fma_f32 v[250:251], v[10:11], v[186:187], v[250:251]
	v_pk_mul_f32 v[254:255], v[204:205], v[198:199] op_sel_hi:[0,1]
	v_add_f32_e32 v14, v250, v251
	v_pk_fma_f32 v[252:253], v[8:9], v[188:189], v[252:253]
	v_pk_fma_f32 v[254:255], v[10:11], v[190:191], v[254:255]
	v_add_f32_dpp v14, v14, v14 quad_perm:[1,0,3,2] row_mask:0xf bank_mask:0xf bound_ctrl:1
	ds_read_b32 v248, v124 offset:3968
	ds_read_b128 v[228:231], v126 offset:2688
	v_add_f32_dpp v14, v14, v14 quad_perm:[2,3,0,1] row_mask:0xf bank_mask:0xf bound_ctrl:1
	ds_read_b128 v[240:243], v126 offset:3456
	ds_read_b128 v[232:235], v126 offset:2944
	v_add_f32_dpp v14, v14, v14 row_half_mirror row_mask:0xf bank_mask:0xf bound_ctrl:1
	ds_read_b128 v[244:247], v126 offset:3712
	ds_read_b128 v[236:239], v126 offset:3200
	v_add_f32_dpp v14, v14, v14 row_mirror row_mask:0xf bank_mask:0xf bound_ctrl:1
	v_pk_fma_f32 v[8:9], v[14:15], v[192:193], v[252:253] op_sel_hi:[0,1,1]
	v_pk_fma_f32 v[10:11], v[14:15], v[194:195], v[254:255] op_sel_hi:[0,1,1]
	s_waitcnt lgkmcnt(6)
	v_pk_mul_f32 v[250:251], v[8:9], v[206:207]
	v_pk_mul_f32 v[252:253], v[226:227], v[218:219] op_sel_hi:[0,1]
	v_pk_fma_f32 v[250:251], v[10:11], v[208:209], v[250:251]
	v_pk_mul_f32 v[254:255], v[226:227], v[220:221] op_sel_hi:[0,1]
	v_add_f32_e32 v14, v250, v251
	v_pk_fma_f32 v[252:253], v[8:9], v[210:211], v[252:253]
	v_pk_fma_f32 v[254:255], v[10:11], v[212:213], v[254:255]
	v_add_f32_dpp v14, v14, v14 quad_perm:[1,0,3,2] row_mask:0xf bank_mask:0xf bound_ctrl:1
	v_pk_mul_f32 v[12:13], v[8:9], v[200:201]
	ds_read_b32 v204, v124 offset:5312
	v_add_f32_dpp v14, v14, v14 quad_perm:[2,3,0,1] row_mask:0xf bank_mask:0xf bound_ctrl:1
	v_pk_fma_f32 v[12:13], v[10:11], v[202:203], v[12:13]
	ds_read_b128 v[184:187], v126 offset:4032
	v_add_f32_dpp v14, v14, v14 row_half_mirror row_mask:0xf bank_mask:0xf bound_ctrl:1
	v_add_f32_e32 v18, v12, v13
	ds_read_b128 v[196:199], v126 offset:4800
	v_add_f32_dpp v14, v14, v14 row_mirror row_mask:0xf bank_mask:0xf bound_ctrl:1
	v_pk_fma_f32 v[8:9], v[14:15], v[214:215], v[252:253] op_sel_hi:[0,1,1]
	v_pk_fma_f32 v[10:11], v[14:15], v[216:217], v[254:255] op_sel_hi:[0,1,1]
	ds_read_b128 v[188:191], v126 offset:4288
	ds_read_b128 v[200:203], v126 offset:5056
	ds_read_b128 v[192:195], v126 offset:4544
	s_waitcnt lgkmcnt(6)
	v_pk_mul_f32 v[250:251], v[8:9], v[228:229]
	v_pk_mul_f32 v[252:253], v[248:249], v[240:241] op_sel_hi:[0,1]
	v_pk_fma_f32 v[250:251], v[10:11], v[230:231], v[250:251]
	v_pk_mul_f32 v[254:255], v[248:249], v[242:243] op_sel_hi:[0,1]
	v_add_f32_e32 v14, v250, v251
	v_pk_fma_f32 v[252:253], v[8:9], v[232:233], v[252:253]
	v_pk_fma_f32 v[254:255], v[10:11], v[234:235], v[254:255]
	v_add_f32_dpp v14, v14, v14 quad_perm:[1,0,3,2] row_mask:0xf bank_mask:0xf bound_ctrl:1
	v_pk_mul_f32 v[12:13], v[8:9], v[222:223]
	ds_read_b32 v226, v124 offset:6656
	v_add_f32_dpp v14, v14, v14 quad_perm:[2,3,0,1] row_mask:0xf bank_mask:0xf bound_ctrl:1
	v_pk_fma_f32 v[12:13], v[10:11], v[224:225], v[12:13]
	ds_read_b128 v[206:209], v126 offset:5376
	v_add_f32_dpp v14, v14, v14 row_half_mirror row_mask:0xf bank_mask:0xf bound_ctrl:1
	v_add_f32_e32 v19, v12, v13
	ds_read_b128 v[218:221], v126 offset:6144
	v_add_f32_dpp v14, v14, v14 row_mirror row_mask:0xf bank_mask:0xf bound_ctrl:1
	v_pk_fma_f32 v[8:9], v[14:15], v[236:237], v[252:253] op_sel_hi:[0,1,1]
	v_pk_fma_f32 v[10:11], v[14:15], v[238:239], v[254:255] op_sel_hi:[0,1,1]
	ds_read_b128 v[210:213], v126 offset:5632
	ds_read_b128 v[222:225], v126 offset:6400
	ds_read_b128 v[214:217], v126 offset:5888
	s_waitcnt lgkmcnt(6)
	v_pk_mul_f32 v[250:251], v[8:9], v[184:185]
	v_pk_mul_f32 v[252:253], v[204:205], v[196:197] op_sel_hi:[0,1]
	v_pk_fma_f32 v[250:251], v[10:11], v[186:187], v[250:251]
	v_pk_mul_f32 v[254:255], v[204:205], v[198:199] op_sel_hi:[0,1]
	v_add_f32_e32 v14, v250, v251
	v_pk_fma_f32 v[252:253], v[8:9], v[188:189], v[252:253]
	v_pk_fma_f32 v[254:255], v[10:11], v[190:191], v[254:255]
	v_add_f32_dpp v14, v14, v14 quad_perm:[1,0,3,2] row_mask:0xf bank_mask:0xf bound_ctrl:1
	v_pk_mul_f32 v[12:13], v[8:9], v[244:245]
	ds_read_b32 v248, v124 offset:8000
	v_add_f32_dpp v14, v14, v14 quad_perm:[2,3,0,1] row_mask:0xf bank_mask:0xf bound_ctrl:1
	v_pk_fma_f32 v[12:13], v[10:11], v[246:247], v[12:13]
	ds_read_b128 v[228:231], v126 offset:6720
	v_add_f32_dpp v14, v14, v14 row_half_mirror row_mask:0xf bank_mask:0xf bound_ctrl:1
	v_add_f32_e32 v20, v12, v13
	ds_read_b128 v[240:243], v126 offset:7488
	v_add_f32_dpp v14, v14, v14 row_mirror row_mask:0xf bank_mask:0xf bound_ctrl:1
	v_pk_fma_f32 v[8:9], v[14:15], v[192:193], v[252:253] op_sel_hi:[0,1,1]
	v_pk_fma_f32 v[10:11], v[14:15], v[194:195], v[254:255] op_sel_hi:[0,1,1]
	ds_read_b128 v[232:235], v126 offset:6976
	ds_read_b128 v[244:247], v126 offset:7744
	ds_read_b128 v[236:239], v126 offset:7232
	s_waitcnt lgkmcnt(6)
	v_pk_mul_f32 v[250:251], v[8:9], v[206:207]
	v_pk_mul_f32 v[252:253], v[226:227], v[218:219] op_sel_hi:[0,1]
	v_pk_fma_f32 v[250:251], v[10:11], v[208:209], v[250:251]
	v_pk_mul_f32 v[254:255], v[226:227], v[220:221] op_sel_hi:[0,1]
	v_add_f32_e32 v14, v250, v251
	v_pk_fma_f32 v[252:253], v[8:9], v[210:211], v[252:253]
	v_pk_fma_f32 v[254:255], v[10:11], v[212:213], v[254:255]
	v_add_f32_dpp v14, v14, v14 quad_perm:[1,0,3,2] row_mask:0xf bank_mask:0xf bound_ctrl:1
	v_pk_mul_f32 v[12:13], v[8:9], v[200:201]
	ds_read_b32 v204, v124 offset:9344
	v_add_f32_dpp v14, v14, v14 quad_perm:[2,3,0,1] row_mask:0xf bank_mask:0xf bound_ctrl:1
	v_pk_fma_f32 v[12:13], v[10:11], v[202:203], v[12:13]
	ds_read_b128 v[184:187], v126 offset:8064
	v_add_f32_dpp v14, v14, v14 row_half_mirror row_mask:0xf bank_mask:0xf bound_ctrl:1
	v_add_f32_e32 v21, v12, v13
	ds_read_b128 v[196:199], v126 offset:8832
	v_add_f32_dpp v14, v14, v14 row_mirror row_mask:0xf bank_mask:0xf bound_ctrl:1
	v_pk_fma_f32 v[8:9], v[14:15], v[214:215], v[252:253] op_sel_hi:[0,1,1]
	v_pk_fma_f32 v[10:11], v[14:15], v[216:217], v[254:255] op_sel_hi:[0,1,1]
	ds_read_b128 v[188:191], v126 offset:8320
	ds_read_b128 v[200:203], v126 offset:9088
	ds_read_b128 v[192:195], v126 offset:8576
	s_waitcnt lgkmcnt(6)
	v_pk_mul_f32 v[250:251], v[8:9], v[228:229]
	v_pk_mul_f32 v[252:253], v[248:249], v[240:241] op_sel_hi:[0,1]
	v_pk_fma_f32 v[250:251], v[10:11], v[230:231], v[250:251]
	v_pk_mul_f32 v[254:255], v[248:249], v[242:243] op_sel_hi:[0,1]
	v_add_f32_e32 v14, v250, v251
	v_pk_fma_f32 v[252:253], v[8:9], v[232:233], v[252:253]
	v_pk_fma_f32 v[254:255], v[10:11], v[234:235], v[254:255]
	v_add_f32_dpp v14, v14, v14 quad_perm:[1,0,3,2] row_mask:0xf bank_mask:0xf bound_ctrl:1
	v_pk_mul_f32 v[12:13], v[8:9], v[222:223]
	ds_read_b32 v226, v124 offset:10688
	v_add_f32_dpp v14, v14, v14 quad_perm:[2,3,0,1] row_mask:0xf bank_mask:0xf bound_ctrl:1
	v_pk_fma_f32 v[12:13], v[10:11], v[224:225], v[12:13]
	ds_read_b128 v[206:209], v126 offset:9408
	v_add_f32_dpp v14, v14, v14 row_half_mirror row_mask:0xf bank_mask:0xf bound_ctrl:1
	v_add_f32_e32 v22, v12, v13
	ds_read_b128 v[218:221], v126 offset:10176
	v_add_f32_dpp v14, v14, v14 row_mirror row_mask:0xf bank_mask:0xf bound_ctrl:1
	v_pk_fma_f32 v[8:9], v[14:15], v[236:237], v[252:253] op_sel_hi:[0,1,1]
	v_pk_fma_f32 v[10:11], v[14:15], v[238:239], v[254:255] op_sel_hi:[0,1,1]
	ds_read_b128 v[210:213], v126 offset:9664
	ds_read_b128 v[222:225], v126 offset:10432
	ds_read_b128 v[214:217], v126 offset:9920
	s_waitcnt lgkmcnt(6)
	v_pk_mul_f32 v[250:251], v[8:9], v[184:185]
	v_pk_mul_f32 v[252:253], v[204:205], v[196:197] op_sel_hi:[0,1]
	v_pk_fma_f32 v[250:251], v[10:11], v[186:187], v[250:251]
	v_pk_mul_f32 v[254:255], v[204:205], v[198:199] op_sel_hi:[0,1]
	v_add_f32_e32 v14, v250, v251
	v_pk_fma_f32 v[252:253], v[8:9], v[188:189], v[252:253]
	v_pk_fma_f32 v[254:255], v[10:11], v[190:191], v[254:255]
	v_add_f32_dpp v14, v14, v14 quad_perm:[1,0,3,2] row_mask:0xf bank_mask:0xf bound_ctrl:1
	v_pk_mul_f32 v[12:13], v[8:9], v[244:245]
	ds_read_b32 v248, v124 offset:12032
	v_add_f32_dpp v14, v14, v14 quad_perm:[2,3,0,1] row_mask:0xf bank_mask:0xf bound_ctrl:1
	v_pk_fma_f32 v[12:13], v[10:11], v[246:247], v[12:13]
	ds_read_b128 v[228:231], v126 offset:10752
	v_add_f32_dpp v14, v14, v14 row_half_mirror row_mask:0xf bank_mask:0xf bound_ctrl:1
	v_add_f32_e32 v23, v12, v13
	ds_read_b128 v[240:243], v126 offset:11520
	v_add_f32_dpp v14, v14, v14 row_mirror row_mask:0xf bank_mask:0xf bound_ctrl:1
	v_pk_fma_f32 v[8:9], v[14:15], v[192:193], v[252:253] op_sel_hi:[0,1,1]
	v_pk_fma_f32 v[10:11], v[14:15], v[194:195], v[254:255] op_sel_hi:[0,1,1]
	ds_read_b128 v[232:235], v126 offset:11008
	ds_read_b128 v[244:247], v126 offset:11776
	ds_read_b128 v[236:239], v126 offset:11264
	s_waitcnt lgkmcnt(6)
	v_pk_mul_f32 v[250:251], v[8:9], v[206:207]
	v_pk_mul_f32 v[252:253], v[226:227], v[218:219] op_sel_hi:[0,1]
	v_pk_fma_f32 v[250:251], v[10:11], v[208:209], v[250:251]
	v_pk_mul_f32 v[254:255], v[226:227], v[220:221] op_sel_hi:[0,1]
	v_add_f32_e32 v14, v250, v251
	v_pk_fma_f32 v[252:253], v[8:9], v[210:211], v[252:253]
	v_pk_fma_f32 v[254:255], v[10:11], v[212:213], v[254:255]
	v_add_f32_dpp v14, v14, v14 quad_perm:[1,0,3,2] row_mask:0xf bank_mask:0xf bound_ctrl:1
	v_pk_mul_f32 v[12:13], v[8:9], v[200:201]
	ds_read_b32 v204, v124 offset:13376
	v_add_f32_dpp v14, v14, v14 quad_perm:[2,3,0,1] row_mask:0xf bank_mask:0xf bound_ctrl:1
	v_pk_fma_f32 v[12:13], v[10:11], v[202:203], v[12:13]
	ds_read_b128 v[184:187], v126 offset:12096
	v_add_f32_dpp v14, v14, v14 row_half_mirror row_mask:0xf bank_mask:0xf bound_ctrl:1
	v_add_f32_e32 v24, v12, v13
	ds_read_b128 v[196:199], v126 offset:12864
	v_add_f32_dpp v14, v14, v14 row_mirror row_mask:0xf bank_mask:0xf bound_ctrl:1
	v_pk_fma_f32 v[8:9], v[14:15], v[214:215], v[252:253] op_sel_hi:[0,1,1]
	v_pk_fma_f32 v[10:11], v[14:15], v[216:217], v[254:255] op_sel_hi:[0,1,1]
	ds_read_b128 v[188:191], v126 offset:12352
	ds_read_b128 v[200:203], v126 offset:13120
	ds_read_b128 v[192:195], v126 offset:12608
	s_waitcnt lgkmcnt(6)
	v_pk_mul_f32 v[250:251], v[8:9], v[228:229]
	v_pk_mul_f32 v[252:253], v[248:249], v[240:241] op_sel_hi:[0,1]
	v_pk_fma_f32 v[250:251], v[10:11], v[230:231], v[250:251]
	v_pk_mul_f32 v[254:255], v[248:249], v[242:243] op_sel_hi:[0,1]
	v_add_f32_e32 v14, v250, v251
	v_pk_fma_f32 v[252:253], v[8:9], v[232:233], v[252:253]
	v_pk_fma_f32 v[254:255], v[10:11], v[234:235], v[254:255]
	v_add_f32_dpp v14, v14, v14 quad_perm:[1,0,3,2] row_mask:0xf bank_mask:0xf bound_ctrl:1
	v_pk_mul_f32 v[12:13], v[8:9], v[222:223]
	ds_read_b32 v226, v124 offset:14720
	v_add_f32_dpp v14, v14, v14 quad_perm:[2,3,0,1] row_mask:0xf bank_mask:0xf bound_ctrl:1
	v_pk_fma_f32 v[12:13], v[10:11], v[224:225], v[12:13]
	ds_read_b128 v[206:209], v126 offset:13440
	v_add_f32_dpp v14, v14, v14 row_half_mirror row_mask:0xf bank_mask:0xf bound_ctrl:1
	v_add_f32_e32 v25, v12, v13
	ds_read_b128 v[218:221], v126 offset:14208
	v_add_f32_dpp v14, v14, v14 row_mirror row_mask:0xf bank_mask:0xf bound_ctrl:1
	v_pk_fma_f32 v[8:9], v[14:15], v[236:237], v[252:253] op_sel_hi:[0,1,1]
	v_pk_fma_f32 v[10:11], v[14:15], v[238:239], v[254:255] op_sel_hi:[0,1,1]
	ds_read_b128 v[210:213], v126 offset:13696
	ds_read_b128 v[222:225], v126 offset:14464
	ds_read_b128 v[214:217], v126 offset:13952
	s_waitcnt vmcnt(0)
	v_alignbit_b32 v36, v75, v74, 16
	v_and_b32_e32 v41, 0xffff0000, v74
	s_xor_b32 s0, s11, 1
	v_lshlrev_b32_e32 v40, 16, v74
	v_and_b32_e32 v123, 0xffff0000, v75
	v_and_b32_e32 v122, 0xffff0000, v36
	s_mulk_i32 s0, 0x5400
	v_pk_mul_f32 v[34:35], v[0:1], v[40:41]
	v_pk_mul_f32 v[36:37], v[2:3], v[122:123]
	v_add_u32_e32 v84, s0, v79
	v_pk_mul_f32 v[120:121], v[78:79], v[34:35] op_sel_hi:[0,1]
	v_pk_mul_f32 v[82:83], v[78:79], v[36:37] op_sel_hi:[0,1]
	v_lshl_add_u32 v85, v50, 2, v84
	v_xor_b32_e32 v35, 0x80000000, v121
	v_xor_b32_e32 v34, 0x80000000, v120
	v_xor_b32_e32 v37, 0x80000000, v83
	v_xor_b32_e32 v36, 0x80000000, v82
	ds_write_b128 v85, v[34:37]
	v_alignbit_b32 v36, v77, v76, 16
	v_and_b32_e32 v45, 0xffff0000, v76
	v_lshlrev_b32_e32 v44, 16, v76
	v_and_b32_e32 v37, 0xffff0000, v77
	v_and_b32_e32 v36, 0xffff0000, v36
	v_pk_add_f32 v[34:35], v[44:45], 1.0 op_sel_hi:[1,0] neg_lo:[1,0] neg_hi:[1,0]
	v_pk_add_f32 v[36:37], v[36:37], 1.0 op_sel_hi:[1,0] neg_lo:[1,0] neg_hi:[1,0]
	ds_write_b128 v85, v[34:37] offset:256
	v_alignbit_b32 v36, v73, v72, 16
	v_and_b32_e32 v43, 0xffff0000, v72
	v_lshlrev_b32_e32 v42, 16, v72
	v_and_b32_e32 v45, 0xffff0000, v73
	v_and_b32_e32 v44, 0xffff0000, v36
	v_pk_mul_f32 v[34:35], v[120:121], v[42:43]
	v_pk_mul_f32 v[36:37], v[82:83], v[44:45]
	ds_write_b128 v85, v[34:37] offset:512
	v_pk_add_f32 v[34:35], v[42:43], -1.0 op_sel_hi:[1,0]
	v_pk_add_f32 v[36:37], v[44:45], -1.0 op_sel_hi:[1,0]
	v_pk_fma_f32 v[34:35], v[4:5], v[34:35], 1.0 op_sel_hi:[1,1,0]
	v_pk_fma_f32 v[36:37], v[6:7], v[36:37], 1.0 op_sel_hi:[1,1,0]
	v_pk_mul_f32 v[34:35], v[34:35], v[40:41]
	v_pk_mul_f32 v[36:37], v[36:37], v[122:123]
	ds_write_b128 v85, v[34:37] offset:768
	v_alignbit_b32 v34, v63, v62, 16
	v_and_b32_e32 v39, 0xffff0000, v62
	v_lshlrev_b32_e32 v38, 16, v62
	v_and_b32_e32 v41, 0xffff0000, v63
	v_and_b32_e32 v40, 0xffff0000, v34
	v_lshlrev_b32_e32 v34, 16, v102
	v_lshl_add_u32 v35, v48, 2, v84
	ds_write_b128 v85, v[38:41] offset:1024
	ds_write_b32 v35, v34 offset:1280
	s_waitcnt lgkmcnt(12)
	v_pk_mul_f32 v[250:251], v[8:9], v[184:185]
	v_pk_mul_f32 v[252:253], v[204:205], v[196:197] op_sel_hi:[0,1]
	v_pk_fma_f32 v[250:251], v[10:11], v[186:187], v[250:251]
	v_pk_mul_f32 v[254:255], v[204:205], v[198:199] op_sel_hi:[0,1]
	v_add_f32_e32 v14, v250, v251
	v_pk_fma_f32 v[252:253], v[8:9], v[188:189], v[252:253]
	v_pk_fma_f32 v[254:255], v[10:11], v[190:191], v[254:255]
	v_add_f32_dpp v14, v14, v14 quad_perm:[1,0,3,2] row_mask:0xf bank_mask:0xf bound_ctrl:1
	v_pk_mul_f32 v[12:13], v[8:9], v[244:245]
	ds_read_b32 v248, v124 offset:16064
	v_add_f32_dpp v14, v14, v14 quad_perm:[2,3,0,1] row_mask:0xf bank_mask:0xf bound_ctrl:1
	v_pk_fma_f32 v[12:13], v[10:11], v[246:247], v[12:13]
	ds_read_b128 v[228:231], v126 offset:14784
	v_add_f32_dpp v14, v14, v14 row_half_mirror row_mask:0xf bank_mask:0xf bound_ctrl:1
	v_add_f32_e32 v26, v12, v13
	ds_read_b128 v[240:243], v126 offset:15552
	v_add_f32_dpp v14, v14, v14 row_mirror row_mask:0xf bank_mask:0xf bound_ctrl:1
	v_pk_fma_f32 v[8:9], v[14:15], v[192:193], v[252:253] op_sel_hi:[0,1,1]
	v_pk_fma_f32 v[10:11], v[14:15], v[194:195], v[254:255] op_sel_hi:[0,1,1]
	ds_read_b128 v[232:235], v126 offset:15040
	ds_read_b128 v[244:247], v126 offset:15808
	ds_read_b128 v[236:239], v126 offset:15296
	s_waitcnt lgkmcnt(12)
	v_pk_mul_f32 v[250:251], v[8:9], v[206:207]
	v_pk_mul_f32 v[252:253], v[226:227], v[218:219] op_sel_hi:[0,1]
	v_pk_fma_f32 v[250:251], v[10:11], v[208:209], v[250:251]
	v_pk_mul_f32 v[254:255], v[226:227], v[220:221] op_sel_hi:[0,1]
	v_add_f32_e32 v14, v250, v251
	v_pk_fma_f32 v[252:253], v[8:9], v[210:211], v[252:253]
	v_pk_fma_f32 v[254:255], v[10:11], v[212:213], v[254:255]
	v_add_f32_dpp v14, v14, v14 quad_perm:[1,0,3,2] row_mask:0xf bank_mask:0xf bound_ctrl:1
	v_pk_mul_f32 v[12:13], v[8:9], v[200:201]
	ds_read_b32 v204, v124 offset:17408
	v_add_f32_dpp v14, v14, v14 quad_perm:[2,3,0,1] row_mask:0xf bank_mask:0xf bound_ctrl:1
	v_pk_fma_f32 v[12:13], v[10:11], v[202:203], v[12:13]
	ds_read_b128 v[184:187], v126 offset:16128
	v_add_f32_dpp v14, v14, v14 row_half_mirror row_mask:0xf bank_mask:0xf bound_ctrl:1
	v_add_f32_e32 v27, v12, v13
	ds_read_b128 v[196:199], v126 offset:16896
	v_add_f32_dpp v14, v14, v14 row_mirror row_mask:0xf bank_mask:0xf bound_ctrl:1
	v_pk_fma_f32 v[8:9], v[14:15], v[214:215], v[252:253] op_sel_hi:[0,1,1]
	v_pk_fma_f32 v[10:11], v[14:15], v[216:217], v[254:255] op_sel_hi:[0,1,1]
	ds_read_b128 v[188:191], v126 offset:16384
	ds_read_b128 v[200:203], v126 offset:17152
	ds_read_b128 v[192:195], v126 offset:16640
	s_waitcnt lgkmcnt(6)
	v_pk_mul_f32 v[250:251], v[8:9], v[228:229]
	v_pk_mul_f32 v[252:253], v[248:249], v[240:241] op_sel_hi:[0,1]
	v_pk_fma_f32 v[250:251], v[10:11], v[230:231], v[250:251]
	v_pk_mul_f32 v[254:255], v[248:249], v[242:243] op_sel_hi:[0,1]
	v_add_f32_e32 v14, v250, v251
	v_pk_fma_f32 v[252:253], v[8:9], v[232:233], v[252:253]
	v_pk_fma_f32 v[254:255], v[10:11], v[234:235], v[254:255]
	v_add_f32_dpp v14, v14, v14 quad_perm:[1,0,3,2] row_mask:0xf bank_mask:0xf bound_ctrl:1
	v_pk_mul_f32 v[12:13], v[8:9], v[222:223]
	ds_read_b32 v226, v124 offset:18752
	v_add_f32_dpp v14, v14, v14 quad_perm:[2,3,0,1] row_mask:0xf bank_mask:0xf bound_ctrl:1
	v_pk_fma_f32 v[12:13], v[10:11], v[224:225], v[12:13]
	ds_read_b128 v[206:209], v126 offset:17472
	v_add_f32_dpp v14, v14, v14 row_half_mirror row_mask:0xf bank_mask:0xf bound_ctrl:1
	v_add_f32_e32 v28, v12, v13
	ds_read_b128 v[218:221], v126 offset:18240
	v_add_f32_dpp v14, v14, v14 row_mirror row_mask:0xf bank_mask:0xf bound_ctrl:1
	v_pk_fma_f32 v[8:9], v[14:15], v[236:237], v[252:253] op_sel_hi:[0,1,1]
	v_pk_fma_f32 v[10:11], v[14:15], v[238:239], v[254:255] op_sel_hi:[0,1,1]
	ds_read_b128 v[210:213], v126 offset:17728
	ds_read_b128 v[222:225], v126 offset:18496
	ds_read_b128 v[214:217], v126 offset:17984
	s_waitcnt lgkmcnt(6)
	v_pk_mul_f32 v[250:251], v[8:9], v[184:185]
	v_pk_mul_f32 v[252:253], v[204:205], v[196:197] op_sel_hi:[0,1]
	v_pk_fma_f32 v[250:251], v[10:11], v[186:187], v[250:251]
	v_pk_mul_f32 v[254:255], v[204:205], v[198:199] op_sel_hi:[0,1]
	v_add_f32_e32 v14, v250, v251
	v_pk_fma_f32 v[252:253], v[8:9], v[188:189], v[252:253]
	v_pk_fma_f32 v[254:255], v[10:11], v[190:191], v[254:255]
	v_add_f32_dpp v14, v14, v14 quad_perm:[1,0,3,2] row_mask:0xf bank_mask:0xf bound_ctrl:1
	v_pk_mul_f32 v[12:13], v[8:9], v[244:245]
	ds_read_b32 v248, v124 offset:20096
	v_add_f32_dpp v14, v14, v14 quad_perm:[2,3,0,1] row_mask:0xf bank_mask:0xf bound_ctrl:1
	v_pk_fma_f32 v[12:13], v[10:11], v[246:247], v[12:13]
	ds_read_b128 v[228:231], v126 offset:18816
	v_add_f32_dpp v14, v14, v14 row_half_mirror row_mask:0xf bank_mask:0xf bound_ctrl:1
	v_add_f32_e32 v29, v12, v13
	ds_read_b128 v[240:243], v126 offset:19584
	v_add_f32_dpp v14, v14, v14 row_mirror row_mask:0xf bank_mask:0xf bound_ctrl:1
	v_pk_fma_f32 v[8:9], v[14:15], v[192:193], v[252:253] op_sel_hi:[0,1,1]
	v_pk_fma_f32 v[10:11], v[14:15], v[194:195], v[254:255] op_sel_hi:[0,1,1]
	ds_read_b128 v[232:235], v126 offset:19072
	ds_read_b128 v[244:247], v126 offset:19840
	ds_read_b128 v[236:239], v126 offset:19328
	s_waitcnt lgkmcnt(6)
	v_pk_mul_f32 v[250:251], v[8:9], v[206:207]
	v_pk_mul_f32 v[252:253], v[226:227], v[218:219] op_sel_hi:[0,1]
	v_pk_fma_f32 v[250:251], v[10:11], v[208:209], v[250:251]
	v_pk_mul_f32 v[254:255], v[226:227], v[220:221] op_sel_hi:[0,1]
	v_add_f32_e32 v14, v250, v251
	v_pk_fma_f32 v[252:253], v[8:9], v[210:211], v[252:253]
	v_pk_fma_f32 v[254:255], v[10:11], v[212:213], v[254:255]
	v_add_f32_dpp v14, v14, v14 quad_perm:[1,0,3,2] row_mask:0xf bank_mask:0xf bound_ctrl:1
	v_pk_mul_f32 v[12:13], v[8:9], v[200:201]
	ds_read_b32 v204, v124 offset:21440
	v_add_f32_dpp v14, v14, v14 quad_perm:[2,3,0,1] row_mask:0xf bank_mask:0xf bound_ctrl:1
	v_pk_fma_f32 v[12:13], v[10:11], v[202:203], v[12:13]
	ds_read_b128 v[184:187], v126 offset:20160
	v_add_f32_dpp v14, v14, v14 row_half_mirror row_mask:0xf bank_mask:0xf bound_ctrl:1
	v_add_f32_e32 v30, v12, v13
	ds_read_b128 v[196:199], v126 offset:20928
	v_add_f32_dpp v14, v14, v14 row_mirror row_mask:0xf bank_mask:0xf bound_ctrl:1
	v_pk_fma_f32 v[8:9], v[14:15], v[214:215], v[252:253] op_sel_hi:[0,1,1]
	v_pk_fma_f32 v[10:11], v[14:15], v[216:217], v[254:255] op_sel_hi:[0,1,1]
	ds_read_b128 v[188:191], v126 offset:20416
	ds_read_b128 v[200:203], v126 offset:21184
	ds_read_b128 v[192:195], v126 offset:20672
	s_waitcnt lgkmcnt(6)
	v_pk_mul_f32 v[250:251], v[8:9], v[228:229]
	v_pk_mul_f32 v[252:253], v[248:249], v[240:241] op_sel_hi:[0,1]
	v_pk_fma_f32 v[250:251], v[10:11], v[230:231], v[250:251]
	v_pk_mul_f32 v[254:255], v[248:249], v[242:243] op_sel_hi:[0,1]
	v_add_f32_e32 v14, v250, v251
	v_pk_fma_f32 v[252:253], v[8:9], v[232:233], v[252:253]
	v_pk_fma_f32 v[254:255], v[10:11], v[234:235], v[254:255]
	v_add_f32_dpp v14, v14, v14 quad_perm:[1,0,3,2] row_mask:0xf bank_mask:0xf bound_ctrl:1
	v_pk_mul_f32 v[12:13], v[8:9], v[222:223]
	s_nop 0
	v_add_f32_dpp v14, v14, v14 quad_perm:[2,3,0,1] row_mask:0xf bank_mask:0xf bound_ctrl:1
	v_pk_fma_f32 v[12:13], v[10:11], v[224:225], v[12:13]
	s_nop 0
	v_add_f32_dpp v14, v14, v14 row_half_mirror row_mask:0xf bank_mask:0xf bound_ctrl:1
	v_add_f32_e32 v31, v12, v13
	s_nop 0
	v_add_f32_dpp v14, v14, v14 row_mirror row_mask:0xf bank_mask:0xf bound_ctrl:1
	v_pk_fma_f32 v[8:9], v[14:15], v[236:237], v[252:253] op_sel_hi:[0,1,1]
	v_pk_fma_f32 v[10:11], v[14:15], v[238:239], v[254:255] op_sel_hi:[0,1,1]
	s_waitcnt lgkmcnt(0)
	v_pk_mul_f32 v[250:251], v[8:9], v[184:185]
	v_pk_mul_f32 v[252:253], v[204:205], v[196:197] op_sel_hi:[0,1]
	v_pk_fma_f32 v[250:251], v[10:11], v[186:187], v[250:251]
	v_pk_mul_f32 v[254:255], v[204:205], v[198:199] op_sel_hi:[0,1]
	v_add_f32_e32 v14, v250, v251
	v_pk_fma_f32 v[252:253], v[8:9], v[188:189], v[252:253]
	v_pk_fma_f32 v[254:255], v[10:11], v[190:191], v[254:255]
	v_add_f32_dpp v14, v14, v14 quad_perm:[1,0,3,2] row_mask:0xf bank_mask:0xf bound_ctrl:1
	v_pk_mul_f32 v[12:13], v[8:9], v[244:245]
	s_nop 0
	v_add_f32_dpp v14, v14, v14 quad_perm:[2,3,0,1] row_mask:0xf bank_mask:0xf bound_ctrl:1
	v_pk_fma_f32 v[12:13], v[10:11], v[246:247], v[12:13]
	s_nop 0
	v_add_f32_dpp v14, v14, v14 row_half_mirror row_mask:0xf bank_mask:0xf bound_ctrl:1
	v_add_f32_e32 v32, v12, v13
	s_nop 0
	v_add_f32_dpp v14, v14, v14 row_mirror row_mask:0xf bank_mask:0xf bound_ctrl:1
	v_pk_fma_f32 v[8:9], v[14:15], v[192:193], v[252:253] op_sel_hi:[0,1,1]
	v_pk_fma_f32 v[10:11], v[14:15], v[194:195], v[254:255] op_sel_hi:[0,1,1]
	v_pk_mul_f32 v[12:13], v[8:9], v[200:201]
	v_add_f32_dpp v34, v18, v18 row_mirror row_mask:0xf bank_mask:0x3 bound_ctrl:1
	v_pk_fma_f32 v[12:13], v[10:11], v[202:203], v[12:13]
	v_add_f32_dpp v35, v19, v19 row_mirror row_mask:0xf bank_mask:0x3 bound_ctrl:1
	v_add_f32_dpp v36, v20, v20 row_mirror row_mask:0xf bank_mask:0x3 bound_ctrl:1
	v_add_f32_e32 v33, v12, v13
	v_add_f32_dpp v37, v21, v21 row_mirror row_mask:0xf bank_mask:0x3 bound_ctrl:1
	v_add_f32_dpp v38, v22, v22 row_mirror row_mask:0xf bank_mask:0x3 bound_ctrl:1
	v_add_f32_dpp v39, v23, v23 row_mirror row_mask:0xf bank_mask:0x3 bound_ctrl:1
	v_add_f32_dpp v40, v24, v24 row_mirror row_mask:0xf bank_mask:0x3 bound_ctrl:1
	v_add_f32_dpp v41, v25, v25 row_mirror row_mask:0xf bank_mask:0x3 bound_ctrl:1
	v_add_f32_dpp v34, v26, v26 row_mirror row_mask:0xf bank_mask:0xc bound_ctrl:1
	v_add_f32_dpp v35, v27, v27 row_mirror row_mask:0xf bank_mask:0xc bound_ctrl:1
	v_add_f32_dpp v36, v28, v28 row_mirror row_mask:0xf bank_mask:0xc bound_ctrl:1
	v_add_f32_dpp v37, v29, v29 row_mirror row_mask:0xf bank_mask:0xc bound_ctrl:1
	v_add_f32_dpp v38, v30, v30 row_mirror row_mask:0xf bank_mask:0xc bound_ctrl:1
	v_add_f32_dpp v39, v31, v31 row_mirror row_mask:0xf bank_mask:0xc bound_ctrl:1
	v_add_f32_dpp v40, v32, v32 row_mirror row_mask:0xf bank_mask:0xc bound_ctrl:1
	v_add_f32_dpp v41, v33, v33 row_mirror row_mask:0xf bank_mask:0xc bound_ctrl:1
	v_add_f32_dpp v42, v34, v34 row_half_mirror row_mask:0xf bank_mask:0x5 bound_ctrl:1
	v_add_f32_dpp v43, v35, v35 row_half_mirror row_mask:0xf bank_mask:0x5 bound_ctrl:1
	v_add_f32_dpp v44, v36, v36 row_half_mirror row_mask:0xf bank_mask:0x5 bound_ctrl:1
	v_add_f32_dpp v45, v37, v37 row_half_mirror row_mask:0xf bank_mask:0x5 bound_ctrl:1
	v_add_f32_dpp v42, v38, v38 row_half_mirror row_mask:0xf bank_mask:0xa bound_ctrl:1
	v_add_f32_dpp v43, v39, v39 row_half_mirror row_mask:0xf bank_mask:0xa bound_ctrl:1
	v_add_f32_dpp v44, v40, v40 row_half_mirror row_mask:0xf bank_mask:0xa bound_ctrl:1
	v_add_f32_dpp v45, v41, v41 row_half_mirror row_mask:0xf bank_mask:0xa bound_ctrl:1
	v_cndmask_b32_e64 v80, v44, v42, s[42:43]
	v_cndmask_b32_e64 v121, v42, v44, s[42:43]
	v_cndmask_b32_e64 v82, v45, v43, s[42:43]
	v_cndmask_b32_e64 v122, v43, v45, s[42:43]
	v_add_u32_e32 v16, s6, v48
	s_mov_b64 s[0:1], -1
	v_add_f32_dpp v13, v121, v80 quad_perm:[2,3,0,1] row_mask:0xf bank_mask:0xf bound_ctrl:1
	v_add_f32_dpp v14, v122, v82 quad_perm:[2,3,0,1] row_mask:0xf bank_mask:0xf bound_ctrl:1
	s_cmp_gt_u32 s10, 15
	v_cndmask_b32_e64 v12, v13, v14, s[44:45]
	v_mov_b32_e32 v15, 0
	s_nop 1
	v_mov_b32_dpp v15, v12 quad_perm:[1,0,3,2] row_mask:0xf bank_mask:0xf
	s_cbranch_scc0 .LBB0_776
	v_add_u32_e32 v12, 0xffffff00, v16
	v_cndmask_b32_e64 v12, v101, v12, s[46:47]
	v_add_u32_e32 v12, v12, v98
	s_mov_b64 s[0:1], 0

	.amdhsa_kernel _Z14fwd_megakernel1P
		.amdhsa_group_segment_fixed_size 16
		.amdhsa_private_segment_fixed_size 0
		.amdhsa_kernarg_size 512
		.amdhsa_user_sgpr_count 2
		.amdhsa_user_sgpr_dispatch_ptr 0
		.amdhsa_user_sgpr_queue_ptr 0
		.amdhsa_user_sgpr_kernarg_segment_ptr 1
		.amdhsa_user_sgpr_dispatch_id 0
		.amdhsa_user_sgpr_kernarg_preload_length 0
		.amdhsa_user_sgpr_kernarg_preload_offset 0
		.amdhsa_user_sgpr_private_segment_size 0
		.amdhsa_uses_dynamic_stack 0
		.amdhsa_enable_private_segment 0
		.amdhsa_system_sgpr_workgroup_id_x 1
		.amdhsa_system_sgpr_workgroup_id_y 0
		.amdhsa_system_sgpr_workgroup_id_z 0
		.amdhsa_system_sgpr_workgroup_info 0
		.amdhsa_system_vgpr_workitem_id 2
		.amdhsa_next_free_vgpr 256
		.amdhsa_next_free_sgpr 102
		.amdhsa_accum_offset 256
		.amdhsa_reserve_vcc 1
		.amdhsa_float_round_mode_32 0
		.amdhsa_float_round_mode_16_64 0
		.amdhsa_float_denorm_mode_32 3
		.amdhsa_float_denorm_mode_16_64 3
		.amdhsa_dx10_clamp 1
		.amdhsa_ieee_mode 1
		.amdhsa_fp16_overflow 0
		.amdhsa_tg_split 0
		.amdhsa_exception_fp_ieee_invalid_op 0
		.amdhsa_exception_fp_denorm_src 0
		.amdhsa_exception_fp_ieee_div_zero 0
		.amdhsa_exception_fp_ieee_overflow 0
		.amdhsa_exception_fp_ieee_underflow 0
		.amdhsa_exception_fp_ieee_inexact 0
		.amdhsa_exception_int_div_zero 0
	.end_amdhsa_kernel

amdhsa.kernels:
  - .agpr_count:     0
    .args:
      - .offset:         0
        .size:           256
        .value_kind:     by_value
      - .offset:         256
        .size:           4
        .value_kind:     hidden_block_count_x
      - .offset:         260
        .size:           4
        .value_kind:     hidden_block_count_y
      - .offset:         264
        .size:           4
        .value_kind:     hidden_block_count_z
      - .offset:         268
        .size:           2
        .value_kind:     hidden_group_size_x
      - .offset:         270
        .size:           2
        .value_kind:     hidden_group_size_y
      - .offset:         272
        .size:           2
        .value_kind:     hidden_group_size_z
      - .offset:         274
        .size:           2
        .value_kind:     hidden_remainder_x
      - .offset:         276
        .size:           2
        .value_kind:     hidden_remainder_y
      - .offset:         278
        .size:           2
        .value_kind:     hidden_remainder_z
      - .offset:         296
        .size:           8
        .value_kind:     hidden_global_offset_x
      - .offset:         304
        .size:           8
        .value_kind:     hidden_global_offset_y
      - .offset:         312
        .size:           8
        .value_kind:     hidden_global_offset_z
      - .offset:         320
        .size:           2
        .value_kind:     hidden_grid_dims
      - .offset:         344
        .size:           8
        .value_kind:     hidden_multigrid_sync_arg
      - .offset:         376
        .size:           4
        .value_kind:     hidden_dynamic_lds_size
    .group_segment_fixed_size: 16
    .kernarg_segment_align: 8
    .kernarg_segment_size: 512
    .language:       OpenCL C
    .language_version:
      - 2
      - 0
    .max_flat_workgroup_size: 256
    .name:           _Z14fwd_megakernel1P
    .private_segment_fixed_size: 0
    .sgpr_count:     108
    .sgpr_spill_count: 222
    .symbol:         _Z14fwd_megakernel1P.kd
    .uniform_work_group_size: 1
    .uses_dynamic_stack: false
    .vgpr_count:     256
    .vgpr_spill_count: 0
    .wavefront_size: 64
